# v55 plus scalar has-next test in the FFN1 tile header (s_cmp/s_cselect instead of 64-bit v_cmp + v_cndmask)
# speedup vs baseline: 1.0010x; 1.0010x over previous
;     __host__ __device__ bool next(int i, Unit& u) const {
;         const long L = (long)i * G + c; if (L >= nwg) return false;
;         int wgid = (int)L; { const int q = nwg / NXCD, r = nwg % NXCD, xcd = wgid % NXCD, off = wgid / NXCD; wgid = (xcd < r ? xcd * (q + 1) : r * (q + 1) + (xcd - r) * q) + off; }
;         const int nig = wgm * nN, gid = wgid / nig, fm = gid * wgm, gsz = (nM - fm) < wgm ? (nM - fm) : wgm;
;         u.pm = fm + ((wgid % nig) % gsz); u.pn = (wgid % nig) / gsz; return true;
; template <class Epi, class Sched, bool ALIGN_EPI = false, bool SP2 = false>
; __device__ __forceinline__ void gemm_phase(PG8_LAS unsigned char* lds, const Gemm g, const Sched& S, const Epi& E) {
;     ...
;         const bool has_next = S.next(ui + 1, nxt);
;         const char* nA = has_next ? (const char*)g.A + (size_t)nxt.pm * tstep : cA; const char* nB = has_next ? (const char*)g.Bt + (size_t)nxt.pn * tstep : cB;
.LBB0_395:
	s_add_i32 s89, s89, 1
	s_mul_i32 s6, s89, s67
	s_mul_hi_u32 s7, s89, s26
	s_add_i32 s7, s7, s6
	s_mul_i32 s6, s89, s26
	s_add_u32 s6, s6, s2
	s_addc_u32 s7, s7, s33
	s_cmp_lt_u32 s6, 0xb00
	s_cselect_b64 s[8:9], -1, 0
	s_cbranch_scc0 .LBB0_397
	s_ashr_i32 s7, s6, 31
	s_lshr_b32 s7, s7, 29
	s_add_i32 s7, s6, s7
	s_ashr_i32 s16, s7, 3
	s_and_b32 s7, s7, -8
	s_sub_i32 s6, s6, s7
	s_cmp_lt_i32 s6, 0
	s_cselect_b32 s7, s51, 0x160
	s_mul_i32 s6, s7, s6
	s_add_i32 s6, s6, s16
	s_mul_hi_i32 s7, s6, 0x2e8ba2e9
	s_lshr_b32 s16, s7, 31
	s_ashr_i32 s7, s7, 6
	s_add_i32 s7, s7, s16
	s_lshl_b32 s16, s7, 3
	s_mulk_i32 s7, 0x160
	s_sub_i32 s6, s6, s7
	s_lshr_b32 s90, s6, 3
	s_and_b32 s6, s6, 7
	s_add_i32 s91, s6, s16
.LBB0_397:
	s_not_b64 s[6:7], s[8:9]
	s_andn2_b64 vcc, exec, s[8:9]
	s_mov_b64 s[8:9], s[18:19]
	s_cbranch_vccnz .LBB0_399
	s_mul_i32 s8, s91, 0x108000
	s_mul_hi_i32 s9, s91, 0x108000
	s_add_u32 s8, s78, s8
	s_addc_u32 s9, s79, s9
